# GEMM-GEMM and cross-attention seams synchronise only the four workgroups that own the same row blocks (quad barrier on one monotonic counter) instead of the whole XCD
# baseline (speedup 1.0000x reference)
; __device__ __forceinline__ unsigned xb_ld(unsigned* p)              { return __hip_atomic_load(p, __ATOMIC_RELAXED, __HIP_MEMORY_SCOPE_AGENT); }
; __device__ __forceinline__ unsigned xb_add(unsigned* p, unsigned v) { return __hip_atomic_fetch_add(p, v, __ATOMIC_RELAXED, __HIP_MEMORY_SCOPE_AGENT); }
; #define XB_SPIN(cond, bar) do { unsigned _sp = 0; while (cond) { __builtin_amdgcn_s_sleep(1); \
;     if ((++_sp & 255u) == 0u) { if (xb_ld(&(bar)[XB_TMO])) break; if (_sp > XB_SPIN_CAP) { atomicAdd(&(bar)[XB_TMO], 1u); break; } } } } while (0)
; __device__ __forceinline__ void xcd_barrier(const XcdBarrier& b, bool t0) {
;     asm volatile("s_waitcnt vmcnt(0)" ::: "memory");
;     __syncthreads();
;     if (t0) {
;         unsigned* bar = b.bar;
;         __builtin_amdgcn_s_waitcnt(0);
;         unsigned nloc = b.st[0], nx = b.st[1];
;         if (nloc == 0u) { xcd_barrier_complete(bar, b.x, nloc, nx); b.st[0] = nloc; b.st[1] = nx; }
;         const unsigned old = xb_add(&bar[XB_XSUB(b.x)], 1u);
;         const unsigned gen = old / nloc;
;         if (old + 1u == (gen + 1u) * nloc) {
;             __builtin_amdgcn_fence(__ATOMIC_RELEASE, "agent");
;             asm volatile("s_waitcnt vmcnt(0)" ::: "memory");
;             const unsigned og = xb_add(&bar[XB_TOP], 1u);
;             const unsigned tg = og / nx;
;             if (og + 1u == (tg + 1u) * nx) xb_add(&bar[XB_TOPGEN], 1u);
;             else XB_SPIN(xb_ld(&bar[XB_TOPGEN]) == tg, bar);
;             __builtin_amdgcn_fence(__ATOMIC_ACQUIRE, "agent");
;             xb_add(&bar[XB_XGEN(b.x)], 1u);
;             asm volatile("s_waitcnt vmcnt(0)" ::: "memory");
;         } else {
;             XB_SPIN(xb_ld(&bar[XB_XGEN(b.x)]) == gen, bar);
;             __builtin_amdgcn_fence(__ATOMIC_ACQUIRE, "agent");
;             asm volatile("s_waitcnt vmcnt(0)" ::: "memory");
;         }
;     }
;     __syncthreads();
; }
.Lxl0_go:
	s_and_b32 s12, s72, 63
	s_lshl_b32 s12, s12, 2
	s_add_u32 s14, s10, s12
	s_addc_u32 s15, s11, 0
	v_mov_b32_e32 v4, 0x1fa02080
	v_mov_b32_e32 v5, 1
	global_atomic_add v6, v4, v5, s[14:15] sc0
	s_waitcnt vmcnt(0)
	v_readfirstlane_b32 s16, v6
	s_nop 3
	s_lshr_b32 s17, s16, 2
	s_add_i32 s17, s17, 1
	s_lshl_b32 s17, s17, 2
	s_add_i32 s12, s16, 1
	s_cmp_eq_u32 s12, s17
	s_cbranch_scc1 .Lxl0_rel
	s_mov_b32 vcc_lo, 0
.Lxl0_spin:
	global_load_dword v6, v4, s[14:15] sc1
	s_waitcnt vmcnt(0)
	v_readfirstlane_b32 s16, v6
	s_nop 3
	s_cmp_ge_u32 s16, s17
	s_cbranch_scc1 .Lxl0_rel
	s_sleep 1
	s_add_i32 vcc_lo, vcc_lo, 1
	s_cmp_lt_u32 vcc_lo, 0x400000
	s_cbranch_scc1 .Lxl0_spin
